# gridDim==512 guard on the D/F XCD-aware remap (no functional change on MI355X); stack: packed scan, PV-pipelined attention, XCD remaps D/F/A, C2 balance
# baseline (speedup 1.0000x reference)
; __device__ __forceinline__ unsigned char* WS(const Params& p) { unsigned z = 0; asm volatile("" : "+s"(z)); return p.ws + z; }
; __device__ __forceinline__ void run_phase(const Params& p, int ph, char* lds, int mode) {
;     ...
;   const int l = (ph - 1) / 7, sp = (ph - 1) % 7;
;   const float* xin = (l == 0) ? p.x : p.out;
;   switch (sp) {
;     ...
;     case 6: {
;       for (int it = B; it < 1024; it += G) { if (EN(60)) gemm_RES((const bf16_t*)(WS(p) + OFF_U), DFF, (const bf16_t*)(WS(p) + OFF_WDN), p.out, p.out, (bf16_t*)(WS(p) + OFF_XB), (float*)(WS(p) + OFF_RSS), it, lds); __syncthreads(); }
.LBB0_87:
	s_add_i32 s3, s2, -1
	s_mul_hi_i32 s24, s3, 0x92492493
	s_add_i32 s24, s24, s3
	s_lshr_b32 s25, s24, 31
	s_ashr_i32 s24, s24, 2
	s_add_i32 s64, s24, s25
	s_mul_i32 s24, s64, 7
	s_sub_i32 s3, s3, s24
	s_add_i32 s2, s2, 5
	s_cmp_lt_u32 s2, 13
	s_cselect_b64 s[4:5], -1, 0
	v_writelane_b32 v255, s4, 11
	s_cmp_lt_i32 s3, 3
	s_mov_b64 s[24:25], -1
	v_writelane_b32 v255, s5, 12
	v_writelane_b32 v255, s3, 13
	s_cbranch_scc1 .LBB0_152
	v_readlane_b32 s2, v255, 13
	s_cmp_lt_i32 s2, 5
	s_cbranch_scc1 .LBB0_112
	v_readlane_b32 s2, v255, 13
	s_cmp_lt_i32 s2, 6
	s_cbranch_scc1 .LBB0_105
	v_readlane_b32 s2, v255, 13
	s_cmp_eq_u32 s2, 6
	s_cbranch_scc0 .LBB0_104
	v_readlane_b32 s2, v254, 5
	v_readlane_b32 s3, v254, 6
	s_andn2_b64 vcc, exec, s[2:3]
	s_cbranch_vccnz .LBB0_104
	s_waitcnt lgkmcnt(0)
	s_lshl_b32 s30, s77, 4
	s_lshl_b32 s31, s77, 7
	v_readlane_b32 s34, v254, 43
	v_readlane_b32 s35, v254, 58
	v_readlane_b32 s36, v252, 0
	s_nop 0
	s_cmpk_lg_u32 s77, 0x200
	s_cbranch_scc1 .Lxcd_skip1
	s_and_b32 s2, s36, 7
	s_lshl_b32 s2, s2, 3
	s_bfe_u32 s3, s36, 0x30003
	s_or_b32 s2, s2, s3
	s_andn2_b32 s36, s36, 63
	s_or_b32 s36, s36, s2
	s_lshl_b32 s35, s36, 4
	s_lshl_b32 s34, s36, 7
.Lxcd_skip1:
	s_branch .LBB0_94
.LBB0_93:
	s_or_b64 exec, exec, s[26:27]
	s_add_i32 s36, s36, s77
	s_add_i32 s35, s35, s30
	s_add_i32 s34, s34, s31
	s_cmpk_gt_i32 s36, 0x3ff
	s_waitcnt lgkmcnt(0)
	s_barrier
	s_cbranch_scc1 .LBB0_104

; __device__ __forceinline__ unsigned char* WS(const Params& p) { unsigned z = 0; asm volatile("" : "+s"(z)); return p.ws + z; }
; __device__ __forceinline__ int opaque_tid() { int t = threadIdx.x; asm volatile("" : "+v"(t)); return t; }
; __device__ __forceinline__ void run_phase(const Params& p, int ph, char* lds, int mode) {
;     ...
;     case 4: {
;       { float* z = (float*)(WS(p) + OFF_RSS) + 2 * T; for (int i = B * NTHREADS + opaque_tid(); i < 2 * T; i += G * NTHREADS) z[i] = 0.f; }
;       const bf16_t* wo = (const bf16_t*)(WS(p) + ((l & 1) ? OFF_WOUT2 : OFF_WOUT));
;       for (int it = B; it < 1024; it += G) { if (EN(40)) gemm_RES((const bf16_t*)(WS(p) + OFF_Y), 1024, wo, xin, p.out, (bf16_t*)(WS(p) + OFF_XB), (float*)(WS(p) + OFF_RSS) + T, it, lds); __syncthreads(); }
.LBB0_122:
	s_or_b64 exec, exec, s[24:25]
	v_readlane_b32 s4, v254, 5
	v_readlane_b32 s5, v254, 6
	s_mov_b32 s2, s89
	s_andn2_b64 vcc, exec, s[4:5]
	s_cbranch_vccnz .LBB0_135
	s_add_u32 s3, s46, s2
	s_addc_u32 s25, s47, 0
	s_bitcmp0_b32 s64, 0
	s_mov_b32 s24, 0x568000
	s_cselect_b32 s28, s24, 0xf94c000
	s_add_u32 s24, s3, s28
	v_readlane_b32 s4, v255, 11
	s_addc_u32 s25, s25, 0
	v_readlane_b32 s5, v255, 12
	s_and_b64 s[26:27], s[4:5], exec
	v_readlane_b32 s4, v252, 35
	v_readlane_b32 s18, v252, 49
	v_readlane_b32 s19, v252, 50
	s_cselect_b32 s27, s49, s19
	s_cselect_b32 s26, s48, s18
	s_waitcnt lgkmcnt(0)
	s_lshl_b32 s38, s77, 4
	s_add_u32 s2, s28, s2
	s_addc_u32 s3, 0, 0
	v_readlane_b32 s4, v254, 51
	s_add_u32 s28, s4, s2
	v_readlane_b32 s2, v254, 52
	s_addc_u32 s29, s2, s3
	s_lshl_b32 s39, s77, 7
	v_readlane_b32 s40, v254, 43
	v_readlane_b32 s41, v254, 58
	v_readlane_b32 s42, v252, 0
	v_readlane_b32 s5, v252, 36
	v_readlane_b32 s6, v252, 37
	v_readlane_b32 s7, v252, 38
	v_readlane_b32 s8, v252, 39
	v_readlane_b32 s9, v252, 40
	v_readlane_b32 s10, v252, 41
	v_readlane_b32 s11, v252, 42
	v_readlane_b32 s12, v252, 43
	v_readlane_b32 s13, v252, 44
	v_readlane_b32 s14, v252, 45
	v_readlane_b32 s15, v252, 46
	v_readlane_b32 s16, v252, 47
	v_readlane_b32 s17, v252, 48
	s_nop 0
	s_cmpk_lg_u32 s77, 0x200
	s_cbranch_scc1 .Lxcd_skip2
	s_and_b32 s2, s42, 7
	s_lshl_b32 s2, s2, 3
	s_bfe_u32 s3, s42, 0x30003
	s_or_b32 s2, s2, s3
	s_andn2_b32 s42, s42, 63
	s_or_b32 s42, s42, s2
	s_lshl_b32 s41, s42, 4
	s_lshl_b32 s40, s42, 7
.Lxcd_skip2:
	s_branch .LBB0_125
.LBB0_124:
	s_or_b64 exec, exec, s[34:35]
	s_add_i32 s42, s42, s77
	s_add_i32 s41, s41, s38
	s_add_i32 s40, s40, s39
	s_cmpk_gt_i32 s42, 0x3ff
	s_waitcnt lgkmcnt(0)
	s_barrier
	s_cbranch_scc1 .LBB0_135
